# gate_prompt output pass: u/g rows via coalesced loads staged in wave-private LDS; X3 sample_out_block K loop staged too
# speedup vs baseline: 1.0033x; 1.0033x over previous
; __device__ __forceinline__ void gate_prompt_item(LAS unsigned char* lds, const bf16_t* z, bf16_t* mix, const float* w_s, const float* b_s,
;                                                  const float* lnv_g, const float* lnv_b, int item, int tid) {
;     ...
;     const float bias = b_s[gr * 128 + i];
;     const size_t tok = tok0 + i;
;     u32x2 uq[16], gq[16];
; #pragma unroll
;     for (int ct = 0; ct < 16; ++ct) { const int col = gr * 256 + 16 * ct + 4 * g; uq[ct] = *(const u32x2*)(z + tok * EIN + 2304 + col); gq[ct] = *(const u32x2*)(z + tok * EIN + 4352 + col); }
; #pragma unroll
.LBB0_921:
	s_or_b64 exec, exec, s[84:85]
	v_add_u32_e32 v2, s80, v44
	v_readlane_b32 s84, v255, 7
	v_ashrrev_i32_e32 v3, 31, v2
	v_readlane_b32 s85, v255, 8
	v_mov_b64_e32 v[20:21], s[96:97]
	v_or_b32_e32 v51, s8, v154
	v_lshl_add_u64 v[2:3], v[2:3], 2, s[84:85]
	global_load_dword v52, v[2:3], off
	v_lshl_add_u64 v[2:3], s[82:83], 0, v[44:45]
	v_mad_u64_u32 v[20:21], s[8:9], v2, s67, v[20:21]
	v_mov_b32_e32 v0, v21
	v_mad_u64_u32 v[22:23], s[8:9], v3, s67, v[0:1]
	v_mov_b32_e32 v21, v22
	s_mov_b64 s[8:9], 0x1200
	v_lshl_add_u64 v[22:23], v[20:21], 0, s[8:9]
	s_mov_b64 s[8:9], 0x2200
	v_lshlrev_b32_e32 v0, 1, v51
	v_lshl_add_u64 v[20:21], v[20:21], 0, s[8:9]
	v_readfirstlane_b32 s8, v139
	s_lshr_b32 s8, s8, 6
	s_lshl_b32 s9, s8, 4
	s_add_i32 s9, s9, s82
	s_mul_i32 s9, s9, 0x2a00
	s_lshl_b32 s98, s80, 2
	s_add_i32 s9, s9, s98
	s_add_u32 s98, s96, s9
	s_addc_u32 s99, s97, 0
	s_add_u32 s98, s98, 0x1200
	s_addc_u32 s99, s99, 0
	s_add_u32 s100, s98, 0x1000
	s_addc_u32 s101, s99, 0
	v_lshrrev_b32_e32 v155, 5, v215
	v_and_b32_e32 v156, 31, v215
	v_mul_u32_u24_e32 v157, 0x210, v155
	v_lshl_add_u32 v157, v156, 4, v157
	v_mul_u32_u24_e32 v155, 0x2a00, v155
	v_lshl_add_u32 v155, v156, 4, v155
	s_mul_i32 s9, s8, 0x2100
	s_add_i32 s9, s9, 0x10c00
	v_add_u32_e32 v157, s9, v157
	v_and_b32_e32 v198, 15, v215
	v_mul_u32_u24_e32 v198, 0x210, v198
	v_lshrrev_b32_e32 v156, 4, v215
	v_lshl_add_u32 v198, v156, 3, v198
	v_add_u32_e32 v198, s9, v198
	global_load_dwordx4 v[158:161], v155, s[98:99]
	s_add_u32 s98, s98, 0x5400
	s_addc_u32 s99, s99, 0
	global_load_dwordx4 v[162:165], v155, s[98:99]
	s_add_u32 s98, s98, 0x5400
	s_addc_u32 s99, s99, 0
	global_load_dwordx4 v[166:169], v155, s[98:99]
	s_add_u32 s98, s98, 0x5400
	s_addc_u32 s99, s99, 0
	global_load_dwordx4 v[170:173], v155, s[98:99]
	s_add_u32 s98, s98, 0x5400
	s_addc_u32 s99, s99, 0
	global_load_dwordx4 v[174:177], v155, s[98:99]
	s_add_u32 s98, s98, 0x5400
	s_addc_u32 s99, s99, 0
	global_load_dwordx4 v[178:181], v155, s[98:99]
	s_add_u32 s98, s98, 0x5400
	s_addc_u32 s99, s99, 0
	global_load_dwordx4 v[182:185], v155, s[98:99]
	s_add_u32 s98, s98, 0x5400
	s_addc_u32 s99, s99, 0
	global_load_dwordx4 v[186:189], v155, s[98:99]
	global_load_dwordx4 v[190:193], v155, s[100:101]
	s_add_u32 s100, s100, 0x5400
	s_addc_u32 s101, s101, 0
	global_load_dwordx4 v[194:197], v155, s[100:101]
	s_add_u32 s100, s100, 0x5400
	s_addc_u32 s101, s101, 0
	global_load_dwordx4 v[226:229], v155, s[100:101]
	s_add_u32 s100, s100, 0x5400
	s_addc_u32 s101, s101, 0
	global_load_dwordx4 v[230:233], v155, s[100:101]
	s_add_u32 s100, s100, 0x5400
	s_addc_u32 s101, s101, 0
	global_load_dwordx4 v[234:237], v155, s[100:101]
	s_add_u32 s100, s100, 0x5400
	s_addc_u32 s101, s101, 0
	global_load_dwordx4 v[238:241], v155, s[100:101]
	s_add_u32 s100, s100, 0x5400
	s_addc_u32 s101, s101, 0
	global_load_dwordx4 v[242:245], v155, s[100:101]
	s_add_u32 s100, s100, 0x5400
	s_addc_u32 s101, s101, 0
	global_load_dwordx4 v[246:249], v155, s[100:101]
	s_waitcnt vmcnt(8)
	ds_write_b128 v157, v[158:161]
	ds_write_b128 v157, v[162:165] offset:1056
	ds_write_b128 v157, v[166:169] offset:2112
	ds_write_b128 v157, v[170:173] offset:3168
	ds_write_b128 v157, v[174:177] offset:4224
	ds_write_b128 v157, v[178:181] offset:5280
	ds_write_b128 v157, v[182:185] offset:6336
	ds_write_b128 v157, v[186:189] offset:7392
	ds_read_b64 v[62:63], v198
	ds_read_b64 v[114:115], v198 offset:32
	ds_read_b64 v[110:111], v198 offset:64
	ds_read_b64 v[106:107], v198 offset:96
	ds_read_b64 v[102:103], v198 offset:128
	ds_read_b64 v[98:99], v198 offset:160
	ds_read_b64 v[94:95], v198 offset:192
	ds_read_b64 v[90:91], v198 offset:224
	ds_read_b64 v[86:87], v198 offset:256
	ds_read_b64 v[80:81], v198 offset:288
	ds_read_b64 v[76:77], v198 offset:320
	ds_read_b64 v[72:73], v198 offset:352
	ds_read_b64 v[68:69], v198 offset:384
	ds_read_b64 v[64:65], v198 offset:416
	ds_read_b64 v[58:59], v198 offset:448
	ds_read_b64 v[54:55], v198 offset:480
	s_waitcnt vmcnt(0)
	s_waitcnt lgkmcnt(0)
	ds_write_b128 v157, v[190:193]
	ds_write_b128 v157, v[194:197] offset:1056
	ds_write_b128 v157, v[226:229] offset:2112
	ds_write_b128 v157, v[230:233] offset:3168
	ds_write_b128 v157, v[234:237] offset:4224
	ds_write_b128 v157, v[238:241] offset:5280
	ds_write_b128 v157, v[242:245] offset:6336
	ds_write_b128 v157, v[246:249] offset:7392
	ds_read_b64 v[118:119], v198
	ds_read_b64 v[116:117], v198 offset:32
	ds_read_b64 v[112:113], v198 offset:64
	ds_read_b64 v[108:109], v198 offset:96
	ds_read_b64 v[104:105], v198 offset:128
	ds_read_b64 v[100:101], v198 offset:160
	ds_read_b64 v[96:97], v198 offset:192
	ds_read_b64 v[92:93], v198 offset:224
	ds_read_b64 v[88:89], v198 offset:256
	ds_read_b64 v[84:85], v198 offset:288
	ds_read_b64 v[78:79], v198 offset:320
	ds_read_b64 v[74:75], v198 offset:352
	ds_read_b64 v[70:71], v198 offset:384
	ds_read_b64 v[66:67], v198 offset:416
	ds_read_b64 v[60:61], v198 offset:448
	ds_read_b64 v[56:57], v198 offset:480
	s_waitcnt lgkmcnt(0)
	v_mov_b32_e32 v20, v1
	v_mov_b32_e32 v21, v1
	v_mov_b32_e32 v22, v1
	v_mov_b32_e32 v23, v1
	s_and_saveexec_b64 s[8:9], s[6:7]
	s_cbranch_execnz .LBB0_1000
	s_or_b64 exec, exec, s[8:9]
	s_and_saveexec_b64 s[8:9], s[24:25]
	s_cbranch_execnz .LBB0_1001

; #define LAS __attribute__((address_space(3)))
; #define MFMA16(a, b, c) __builtin_amdgcn_mfma_f32_16x16x32_bf16((a), (b), (c), 0, 0, 0)
; __device__ __forceinline__ void sample_out_block(LAS unsigned char* lds, const bf16_t* A, const bf16_t* Bt, int K, bf16_t* xb, float* sspart, int blk, int tid) {
;     ...
;     {
;         const bf16_t* ap = A + (size_t)(r0 + l15) * K + wave * kq + 8 * g;
;         const bf16_t* bp = Bt + (size_t)(64 * cg + l15) * K + wave * kq + 8 * g;
;         bf16x8 af[2][2], bf[2][4], afn[2][2], bfn[2][4];
; #pragma unroll
;         for (int s = 0; s < 2; ++s) {
; #pragma unroll
;             for (int ra = 0; ra < 2; ++ra) af[s][ra] = *(const bf16x8*)(ap + (size_t)(16 * ra) * K + 32 * s);
; #pragma unroll
;             for (int nt = 0; nt < 4; ++nt) bf[s][nt] = *(const bf16x8*)(bp + (size_t)(16 * nt) * K + 32 * s);
;         }
;         for (int k0 = 0; k0 < kq; k0 += 64) {
;             const int k1 = (k0 + 64 < kq) ? k0 + 64 : k0;
; #pragma unroll
;             for (int s = 0; s < 2; ++s) {
; #pragma unroll
;                 for (int ra = 0; ra < 2; ++ra) afn[s][ra] = *(const bf16x8*)(ap + (size_t)(16 * ra) * K + k1 + 32 * s);
; #pragma unroll
;                 for (int nt = 0; nt < 4; ++nt) bfn[s][nt] = *(const bf16x8*)(bp + (size_t)(16 * nt) * K + k1 + 32 * s);
;             }
; #pragma unroll
;             for (int s = 0; s < 2; ++s)
; #pragma unroll
;                 for (int ra = 0; ra < 2; ++ra)
; #pragma unroll
;                     for (int nt = 0; nt < 4; ++nt) acc[ra][nt] = MFMA16(af[s][ra], bf[s][nt], acc[ra][nt]);
; #pragma unroll
;             for (int s = 0; s < 2; ++s) {
; #pragma unroll
;                 for (int ra = 0; ra < 2; ++ra) af[s][ra] = afn[s][ra];
; #pragma unroll
;                 for (int nt = 0; nt < 4; ++nt) bf[s][nt] = bfn[s][nt];
;             }
;         }
;     }
;     LAS f32x4* part = (LAS f32x4*)lds;
; #pragma unroll
;     for (int ra = 0; ra < 2; ++ra)
; #pragma unroll
;         for (int nt = 0; nt < 4; ++nt) part[(wave * 8 + ra * 4 + nt) * 64 + lane] = acc[ra][nt];
;     __syncthreads();
.LBB0_1463:
	s_and_b32 s19, s26, 0xffffffe0
	s_addk_i32 s19, 0x2000
	s_and_b32 s18, s26, 31
	v_or_b32_e32 v8, s19, v30
	v_ashrrev_i32_e32 v9, 31, v8
	s_lshl_b32 s20, s18, 6
	v_lshlrev_b64 v[8:9], 10, v[8:9]
	v_or_b32_e32 v0, s20, v30
	v_lshl_add_u64 v[28:29], v[2:3], 0, v[8:9]
	v_lshlrev_b32_e32 v0, 10, v0
	v_lshl_add_u64 v[42:43], v[4:5], 0, v[0:1]
	v_add_co_u32_e32 v66, vcc, 0x4000, v28
	s_mov_b64 s[8:9], vcc
	v_add_co_u32_e32 v24, vcc, 0x4000, v42
	v_readfirstlane_b32 s36, v139
	s_lshr_b32 s36, s36, 6
	s_and_b32 s37, s26, 0xffffffe0
	s_addk_i32 s37, 0x2000
	s_and_b32 s38, s26, 31
	s_lshl_b32 s38, s38, 6
	s_lshl_b32 s39, s37, 10
	s_mul_i32 s40, s36, 0x80
	s_add_u32 s42, s16, s39
	s_addc_u32 s43, s17, 0
	s_add_u32 s42, s42, s40
	s_addc_u32 s43, s43, 0
	s_lshl_b32 s41, s24, 1
	s_lshl_b32 s39, s38, 10
	s_add_u32 s44, s22, s41
	s_addc_u32 s45, s23, 0
	s_add_u32 s44, s44, s39
	s_addc_u32 s45, s45, 0
	s_add_u32 s44, s44, s40
	s_addc_u32 s45, s45, 0
	v_lshrrev_b32_e32 v227, 3, v215
	v_and_b32_e32 v228, 7, v215
	v_lshlrev_b32_e32 v198, 10, v227
	v_lshl_add_u32 v198, v228, 4, v198
	v_add_u32_e32 v199, 0x2000, v198
	v_add_u32_e32 v200, 0x4000, v198
	v_add_u32_e32 v201, 0x6000, v198
	v_add_u32_e32 v202, 0x8000, v198
	v_add_u32_e32 v203, 0xa000, v198
	v_add_u32_e32 v204, 0xc000, v198
	v_add_u32_e32 v205, 0xe000, v198
	s_lshl_b32 s46, s36, 13
	s_mul_i32 s47, s36, 0x1800
	s_add_i32 s47, s47, 0x10000
	v_mul_u32_u24_e32 v206, 0x90, v227
	v_lshl_add_u32 v206, v228, 4, v206
	v_add_u32_e32 v207, s47, v206
	v_add_u32_e32 v206, s46, v206
	v_and_b32_e32 v227, 15, v215
	v_lshrrev_b32_e32 v228, 4, v215
	v_mul_u32_u24_e32 v208, 0x90, v227
	v_lshl_add_u32 v208, v228, 4, v208
	v_add_u32_e32 v209, s47, v208
	v_add_u32_e32 v208, s46, v208
	v_add_u32_e32 v226, 0x1b00, v208
	v_subrev_u32_e32 v228, 0x480, v209
	v_cmp_gt_u32_e32 vcc, 8, v227
	v_cndmask_b32_e32 v226, v228, v226, vcc
	global_load_dwordx4 v[34:37], v198, s[42:43]
	global_load_dwordx4 v[38:41], v199, s[42:43]
	global_load_dwordx4 v[42:45], v200, s[42:43]
	global_load_dwordx4 v[46:49], v201, s[42:43]
	global_load_dwordx4 v[50:53], v198, s[44:45]
	global_load_dwordx4 v[54:57], v199, s[44:45]
	global_load_dwordx4 v[58:61], v200, s[44:45]
	global_load_dwordx4 v[62:65], v201, s[44:45]
	global_load_dwordx4 v[66:69], v202, s[44:45]
	global_load_dwordx4 v[70:73], v203, s[44:45]
	global_load_dwordx4 v[74:77], v204, s[44:45]
	global_load_dwordx4 v[78:81], v205, s[44:45]
	s_waitcnt vmcnt(0)
	ds_write_b128 v206, v[34:37]
	ds_write_b128 v206, v[38:41] offset:1152
	ds_write_b128 v206, v[42:45] offset:2304
	ds_write_b128 v206, v[46:49] offset:3456
	ds_write_b128 v206, v[50:53] offset:4608
	ds_write_b128 v206, v[54:57] offset:5760
	ds_write_b128 v206, v[58:61] offset:6912
	ds_write_b128 v207, v[62:65]
	ds_write_b128 v207, v[66:69] offset:1152
	ds_write_b128 v207, v[70:73] offset:2304
	ds_write_b128 v207, v[74:77] offset:3456
	ds_write_b128 v207, v[78:81] offset:4608
	ds_read_b128 v[146:149], v208 offset:0
	ds_read_b128 v[150:153], v208 offset:2304
	ds_read_b128 v[154:157], v208 offset:4608
	ds_read_b128 v[158:161], v226
	ds_read_b128 v[162:165], v209 offset:1152
	ds_read_b128 v[166:169], v209 offset:3456
	ds_read_b128 v[170:173], v208 offset:64
	ds_read_b128 v[174:177], v208 offset:2368
	ds_read_b128 v[178:181], v208 offset:4672
	ds_read_b128 v[182:185], v226 offset:64
	ds_read_b128 v[186:189], v209 offset:1216
	ds_read_b128 v[190:193], v209 offset:3520
	s_waitcnt lgkmcnt(6)
	v_mfma_f32_16x16x32_bf16 v[8:11], v[146:149], v[154:157], 0
	v_mfma_f32_16x16x32_bf16 v[12:15], v[146:149], v[158:161], 0
	v_mfma_f32_16x16x32_bf16 v[16:19], v[146:149], v[162:165], 0
	v_mfma_f32_16x16x32_bf16 v[20:23], v[146:149], v[166:169], 0
	v_mfma_f32_16x16x32_bf16 v[24:27], v[150:153], v[154:157], 0
	v_mfma_f32_16x16x32_bf16 v[130:133], v[150:153], v[158:161], 0
	v_mfma_f32_16x16x32_bf16 v[134:137], v[150:153], v[162:165], 0
	v_mfma_f32_16x16x32_bf16 v[194:197], v[150:153], v[166:169], 0
	s_waitcnt lgkmcnt(0)
	v_mfma_f32_16x16x32_bf16 v[8:11], v[170:173], v[178:181], v[8:11]
	v_mfma_f32_16x16x32_bf16 v[12:15], v[170:173], v[182:185], v[12:15]
	v_mfma_f32_16x16x32_bf16 v[16:19], v[170:173], v[186:189], v[16:19]
	v_mfma_f32_16x16x32_bf16 v[20:23], v[170:173], v[190:193], v[20:23]
	v_mfma_f32_16x16x32_bf16 v[24:27], v[174:177], v[178:181], v[24:27]
	v_mfma_f32_16x16x32_bf16 v[130:133], v[174:177], v[182:185], v[130:133]
	v_mfma_f32_16x16x32_bf16 v[134:137], v[174:177], v[186:189], v[134:137]
	v_mfma_f32_16x16x32_bf16 v[194:197], v[174:177], v[190:193], v[194:197]
	s_nop 7
	s_nop 7
	ds_write_b128 v32, v[8:11]
	ds_write_b128 v32, v[12:15] offset:1024
	ds_write_b128 v32, v[16:19] offset:2048
	ds_write_b128 v32, v[20:23] offset:3072
	ds_write_b128 v32, v[24:27] offset:4096
	ds_write_b128 v32, v[130:133] offset:5120
	ds_write_b128 v32, v[134:137] offset:6144
	ds_write_b128 v32, v[194:197] offset:7168
	s_waitcnt lgkmcnt(0)
	s_barrier
	s_and_saveexec_b64 s[8:9], s[4:5]
	s_cbranch_execz .LBB0_1462
; __device__ __forceinline__ float bf1(bf16_t h) { return __uint_as_float((unsigned)h << 16); }
; __device__ __forceinline__ bf16_t f2bf(float f) { return (bf16_t)(pk2(f, 0.f) & 0xffffu); }
; __device__ __forceinline__ void sample_out_block(LAS unsigned char* lds, const bf16_t* A, const bf16_t* Bt, int K, bf16_t* xb, float* sspart, int blk, int tid) {
;     ...
;     if (wave < 2) {
;         const int ra = wave;
;         f32x4 sum[4];
; #pragma unroll
;         for (int nt = 0; nt < 4; ++nt) {
;             sum[nt] = part[(0 * 8 + ra * 4 + nt) * 64 + lane];
; #pragma unroll
;             for (int w = 1; w < 8; ++w) sum[nt] += part[(w * 8 + ra * 4 + nt) * 64 + lane];
;         }
;         float ss[4] = {0.f, 0.f, 0.f, 0.f};
; #pragma unroll
;         for (int j = 0; j < 4; ++j)
; #pragma unroll
;             for (int nt = 0; nt < 4; ++nt) {
;                 bf16_t* xp = xb + (size_t)(r0 + 16 * ra + 4 * g + j) * 2048 + 64 * cg + 16 * nt + l15;
;                 const bf16_t nv = f2bf(bf1(*xp) + sum[nt][j]);
;                 *xp = nv; const float r = bf1(nv); ss[j] += r * r;
	v_add_u32_e32 v170, s19, v31
	v_lshlrev_b32_e32 v170, 12, v170
	s_lshl_b32 s36, s20, 1
	v_add_u32_e32 v170, s36, v170
	v_mov_b32_e32 v171, 0
	s_mov_b64 s[38:39], 0x1000
	v_lshl_add_u64 v[162:163], v[6:7], 0, v[170:171]
	v_lshl_add_u64 v[164:165], v[162:163], 0, s[38:39]
	v_lshl_add_u64 v[166:167], v[164:165], 0, s[38:39]
	v_lshl_add_u64 v[168:169], v[166:167], 0, s[38:39]
	global_load_ushort v146, v[162:163], off
	global_load_ushort v147, v[162:163], off offset:32
	global_load_ushort v148, v[162:163], off offset:64
	global_load_ushort v149, v[162:163], off offset:96
	global_load_ushort v150, v[164:165], off
	global_load_ushort v151, v[164:165], off offset:32
	global_load_ushort v152, v[164:165], off offset:64
	global_load_ushort v153, v[164:165], off offset:96
	global_load_ushort v154, v[166:167], off
	global_load_ushort v155, v[166:167], off offset:32
	global_load_ushort v156, v[166:167], off offset:64
	global_load_ushort v157, v[166:167], off offset:96
	global_load_ushort v158, v[168:169], off
	global_load_ushort v159, v[168:169], off offset:32
	global_load_ushort v160, v[168:169], off offset:64
	global_load_ushort v161, v[168:169], off offset:96
	ds_read_b128 v[8:11], v33
	ds_read_b128 v[12:15], v33 offset:8192
	s_lshl_b32 s80, s20, 1
	v_lshl_add_u64 v[28:29], v[6:7], 0, s[80:81]
	s_lshl_b32 s18, s18, 2
	s_add_u32 s18, s14, s18
	s_waitcnt lgkmcnt(0)
	v_pk_add_f32 v[14:15], v[10:11], v[14:15]
	v_pk_add_f32 v[12:13], v[8:9], v[12:13]
	ds_read_b128 v[8:11], v33 offset:16384
	s_waitcnt lgkmcnt(0)
	v_pk_add_f32 v[14:15], v[14:15], v[10:11]
	v_pk_add_f32 v[12:13], v[12:13], v[8:9]
	ds_read_b128 v[8:11], v33 offset:24576
	s_waitcnt lgkmcnt(0)
	v_pk_add_f32 v[14:15], v[14:15], v[10:11]
	v_pk_add_f32 v[12:13], v[12:13], v[8:9]
	ds_read_b128 v[8:11], v33 offset:32768
	s_waitcnt lgkmcnt(0)
	v_pk_add_f32 v[14:15], v[14:15], v[10:11]
	v_pk_add_f32 v[12:13], v[12:13], v[8:9]
	ds_read_b128 v[8:11], v33 offset:40960
	s_waitcnt lgkmcnt(0)
	v_pk_add_f32 v[14:15], v[14:15], v[10:11]
	v_pk_add_f32 v[12:13], v[12:13], v[8:9]
	ds_read_b128 v[8:11], v33 offset:49152
	s_waitcnt lgkmcnt(0)
	v_pk_add_f32 v[14:15], v[14:15], v[10:11]
	v_pk_add_f32 v[16:17], v[12:13], v[8:9]
	ds_read_b128 v[8:11], v33 offset:57344
	s_waitcnt lgkmcnt(0)
	v_pk_add_f32 v[12:13], v[14:15], v[10:11]
	v_pk_add_f32 v[20:21], v[16:17], v[8:9]
	ds_read_b128 v[8:11], v33 offset:1024
	ds_read_b128 v[14:17], v33 offset:9216
	s_waitcnt lgkmcnt(0)
	v_pk_add_f32 v[16:17], v[10:11], v[16:17]
	v_pk_add_f32 v[14:15], v[8:9], v[14:15]
	ds_read_b128 v[8:11], v33 offset:17408
	s_waitcnt lgkmcnt(0)
	v_pk_add_f32 v[16:17], v[16:17], v[10:11]
	v_pk_add_f32 v[14:15], v[14:15], v[8:9]
	ds_read_b128 v[8:11], v33 offset:25600
	s_waitcnt lgkmcnt(0)
	v_pk_add_f32 v[16:17], v[16:17], v[10:11]
	v_pk_add_f32 v[14:15], v[14:15], v[8:9]
	ds_read_b128 v[8:11], v33 offset:33792
	s_waitcnt lgkmcnt(0)
	v_pk_add_f32 v[16:17], v[16:17], v[10:11]
	v_pk_add_f32 v[14:15], v[14:15], v[8:9]
	ds_read_b128 v[8:11], v33 offset:41984
	s_waitcnt lgkmcnt(0)
	v_pk_add_f32 v[16:17], v[16:17], v[10:11]
	v_pk_add_f32 v[14:15], v[14:15], v[8:9]
	ds_read_b128 v[8:11], v33 offset:50176
	s_waitcnt lgkmcnt(0)
	v_pk_add_f32 v[16:17], v[16:17], v[10:11]
	v_pk_add_f32 v[14:15], v[14:15], v[8:9]
	ds_read_b128 v[8:11], v33 offset:58368
	s_waitcnt lgkmcnt(0)
	v_pk_add_f32 v[18:19], v[16:17], v[10:11]
	v_pk_add_f32 v[26:27], v[14:15], v[8:9]
	ds_read_b128 v[8:11], v33 offset:2048
	ds_read_b128 v[14:17], v33 offset:10240
	s_waitcnt lgkmcnt(0)
	v_pk_add_f32 v[16:17], v[10:11], v[16:17]
	v_pk_add_f32 v[14:15], v[8:9], v[14:15]
	ds_read_b128 v[8:11], v33 offset:18432
	s_waitcnt lgkmcnt(0)
	v_pk_add_f32 v[16:17], v[16:17], v[10:11]
	v_pk_add_f32 v[14:15], v[14:15], v[8:9]
	ds_read_b128 v[8:11], v33 offset:26624
	s_waitcnt lgkmcnt(0)
	v_pk_add_f32 v[16:17], v[16:17], v[10:11]
	v_pk_add_f32 v[14:15], v[14:15], v[8:9]
	ds_read_b128 v[8:11], v33 offset:34816
	s_waitcnt lgkmcnt(0)
	v_pk_add_f32 v[16:17], v[16:17], v[10:11]
	v_pk_add_f32 v[14:15], v[14:15], v[8:9]
	ds_read_b128 v[8:11], v33 offset:43008
	s_waitcnt lgkmcnt(0)
	v_pk_add_f32 v[16:17], v[16:17], v[10:11]
	v_pk_add_f32 v[14:15], v[14:15], v[8:9]
	ds_read_b128 v[8:11], v33 offset:51200
	s_waitcnt lgkmcnt(0)
	v_pk_add_f32 v[16:17], v[16:17], v[10:11]
	v_pk_add_f32 v[14:15], v[14:15], v[8:9]
	ds_read_b128 v[8:11], v33 offset:59392
	s_waitcnt lgkmcnt(0)
	v_pk_add_f32 v[16:17], v[16:17], v[10:11]
	v_pk_add_f32 v[24:25], v[14:15], v[8:9]
	ds_read_b128 v[8:11], v33 offset:3072
	ds_read_b128 v[34:37], v33 offset:11264
	s_waitcnt lgkmcnt(0)
	v_pk_add_f32 v[14:15], v[10:11], v[36:37]
	v_pk_add_f32 v[22:23], v[8:9], v[34:35]
	ds_read_b128 v[8:11], v33 offset:19456
	ds_read_b128 v[34:37], v33 offset:60416
	s_waitcnt lgkmcnt(1)
	v_pk_add_f32 v[14:15], v[14:15], v[10:11]
	v_pk_add_f32 v[22:23], v[22:23], v[8:9]
	ds_read_b128 v[8:11], v33 offset:27648
	s_waitcnt lgkmcnt(0)
	v_pk_add_f32 v[14:15], v[14:15], v[10:11]
	v_pk_add_f32 v[22:23], v[22:23], v[8:9]
	ds_read_b128 v[8:11], v33 offset:35840
	s_waitcnt lgkmcnt(0)
; __device__ __forceinline__ float bf1(bf16_t h) { return __uint_as_float((unsigned)h << 16); }
; __device__ __forceinline__ bf16_t f2bf(float f) { return (bf16_t)(pk2(f, 0.f) & 0xffffu); }
; __device__ __forceinline__ void sample_out_block(LAS unsigned char* lds, const bf16_t* A, const bf16_t* Bt, int K, bf16_t* xb, float* sspart, int blk, int tid) {
;     ...
;         for (int j = 0; j < 4; ++j)
; #pragma unroll
;             for (int nt = 0; nt < 4; ++nt) {
;                 bf16_t* xp = xb + (size_t)(r0 + 16 * ra + 4 * g + j) * 2048 + 64 * cg + 16 * nt + l15;
;                 const bf16_t nv = f2bf(bf1(*xp) + sum[nt][j]);
;                 *xp = nv; const float r = bf1(nv); ss[j] += r * r;
;             }
; #pragma unroll
;         for (int j = 0; j < 4; ++j) {
;             float s = ss[j];
;             s += __shfl_xor(s, 1); s += __shfl_xor(s, 2); s += __shfl_xor(s, 4); s += __shfl_xor(s, 8);
;             if (l15 == 0) sspart[(size_t)(r0 + 16 * ra + 4 * g + j) * 32 + cg] = s;
;         }
	v_pk_add_f32 v[14:15], v[14:15], v[10:11]
	v_pk_add_f32 v[22:23], v[22:23], v[8:9]
	ds_read_b128 v[8:11], v33 offset:44032
	s_waitcnt lgkmcnt(0)
	v_pk_add_f32 v[14:15], v[14:15], v[10:11]
	v_pk_add_f32 v[22:23], v[22:23], v[8:9]
	ds_read_b128 v[8:11], v33 offset:52224
	s_waitcnt lgkmcnt(0)
	v_pk_add_f32 v[10:11], v[14:15], v[10:11]
	v_pk_add_f32 v[14:15], v[22:23], v[8:9]
	v_pk_add_f32 v[8:9], v[10:11], v[36:37]
	v_add_u32_e32 v10, s19, v31
	v_ashrrev_i32_e32 v11, 31, v10
	v_pk_add_f32 v[22:23], v[14:15], v[34:35]
	v_lshlrev_b64 v[14:15], 12, v[10:11]
	v_lshl_add_u64 v[14:15], v[28:29], 0, v[14:15]
	s_waitcnt vmcnt(0)
	v_mov_b32_e32 v0, v146
	s_addc_u32 s19, s15, 0
	s_waitcnt vmcnt(0)
	v_lshlrev_b32_e32 v0, 16, v0
	v_add_f32_e32 v0, v20, v0
	v_cvt_pk_bf16_f32 v0, v0, s0
	global_store_short v[14:15], v0, off
	v_lshlrev_b32_e32 v20, 16, v0
	v_mov_b32_e32 v0, v147
	v_lshlrev_b32_e32 v0, 16, v0
	v_add_f32_e32 v0, v26, v0
	v_cvt_pk_bf16_f32 v0, v0, s0
	global_store_short v[14:15], v0, off offset:32
	v_lshlrev_b32_e32 v0, 16, v0
	v_mul_f32_e32 v0, v0, v0
	v_fmac_f32_e32 v0, v20, v20
	v_mov_b32_e32 v20, v148
	v_lshlrev_b32_e32 v20, 16, v20
	v_add_f32_e32 v20, v24, v20
	v_cvt_pk_bf16_f32 v20, v20, s0
	global_store_short v[14:15], v20, off offset:64
	v_lshlrev_b32_e32 v20, 16, v20
	v_fmac_f32_e32 v0, v20, v20
	v_mov_b32_e32 v20, v149
	v_lshlrev_b32_e32 v20, 16, v20
	v_add_f32_e32 v20, v22, v20
	v_cvt_pk_bf16_f32 v20, v20, s0
	global_store_short v[14:15], v20, off offset:96
	v_lshlrev_b32_e32 v14, 16, v20
	v_fmac_f32_e32 v0, v14, v14
	v_or_b32_e32 v14, 1, v10
	v_ashrrev_i32_e32 v15, 31, v14
	v_lshlrev_b64 v[34:35], 12, v[14:15]
	v_lshl_add_u64 v[36:37], v[28:29], 0, v[34:35]
	v_mov_b32_e32 v20, v150
	v_lshlrev_b32_e32 v20, 16, v20
	v_add_f32_e32 v20, v21, v20
	v_cvt_pk_bf16_f32 v26, v20, s0
	v_mov_b32_e32 v20, v151
	v_lshlrev_b32_e32 v20, 16, v20
	v_add_f32_e32 v20, v27, v20
	v_cvt_pk_bf16_f32 v27, v20, s0
	v_mov_b32_e32 v20, v152
	v_lshlrev_b32_e32 v20, 16, v20
	v_add_f32_e32 v20, v25, v20
	v_cvt_pk_bf16_f32 v34, v20, s0
	v_mov_b32_e32 v20, v153
	v_lshlrev_b32_e32 v20, 16, v20
	v_add_f32_e32 v20, v23, v20
	v_cvt_pk_bf16_f32 v35, v20, s0
	v_or_b32_e32 v20, 2, v10
	v_ashrrev_i32_e32 v21, 31, v20
	v_lshlrev_b64 v[22:23], 12, v[20:21]
	v_lshl_add_u64 v[22:23], v[28:29], 0, v[22:23]
	v_mov_b32_e32 v24, v154
	v_lshlrev_b32_e32 v24, 16, v24
	v_add_f32_e32 v12, v12, v24
	v_mov_b32_e32 v24, v155
	v_cvt_pk_bf16_f32 v12, v12, s0
	global_store_short v[22:23], v12, off
	global_store_short v[36:37], v26, off
	global_store_short v[36:37], v27, off offset:32
	global_store_short v[36:37], v34, off offset:64
	global_store_short v[36:37], v35, off offset:96
	v_xor_b32_e32 v36, 8, v215
	s_waitcnt vmcnt(5)
	v_lshlrev_b32_e32 v24, 16, v24
	v_add_f32_e32 v18, v18, v24
	v_mov_b32_e32 v24, v156
	v_cvt_pk_bf16_f32 v18, v18, s0
	global_store_short v[22:23], v18, off offset:32
	s_waitcnt vmcnt(1)
	v_lshlrev_b32_e32 v24, 16, v24
	v_add_f32_e32 v16, v16, v24
	v_mov_b32_e32 v24, v157
	v_cvt_pk_bf16_f32 v16, v16, s0
	global_store_short v[22:23], v16, off offset:64
	s_waitcnt vmcnt(1)
	v_lshlrev_b32_e32 v24, 16, v24
	v_add_f32_e32 v8, v8, v24
	v_cvt_pk_bf16_f32 v8, v8, s0
	global_store_short v[22:23], v8, off offset:96
	v_or_b32_e32 v22, 3, v10
	v_ashrrev_i32_e32 v23, 31, v22
	v_lshlrev_b64 v[24:25], 12, v[22:23]
	v_lshl_add_u64 v[24:25], v[28:29], 0, v[24:25]
	v_mov_b32_e32 v28, v158
	v_lshlrev_b32_e32 v28, 16, v28
	v_add_f32_e32 v13, v13, v28
	v_mov_b32_e32 v28, v159
	v_cvt_pk_bf16_f32 v13, v13, s0
	global_store_short v[24:25], v13, off
	s_waitcnt vmcnt(1)
	v_lshlrev_b32_e32 v28, 16, v28
	v_add_f32_e32 v19, v19, v28
	v_mov_b32_e32 v28, v160
	v_cvt_pk_bf16_f32 v19, v19, s0
	global_store_short v[24:25], v19, off offset:32
	s_waitcnt vmcnt(1)
	v_lshlrev_b32_e32 v28, 16, v28
	v_add_f32_e32 v17, v17, v28
	v_mov_b32_e32 v28, v161
	v_cvt_pk_bf16_f32 v17, v17, s0
	global_store_short v[24:25], v17, off offset:64
	s_waitcnt vmcnt(1)
	v_lshlrev_b32_e32 v28, 16, v28
	v_add_f32_e32 v9, v9, v28
	v_cvt_pk_bf16_f32 v9, v9, s0
	global_store_short v[24:25], v9, off offset:96
	v_and_b32_e32 v25, 64, v215
	v_xor_b32_e32 v24, 1, v215
	v_add_u32_e32 v29, 64, v25
	v_cmp_lt_i32_e32 vcc, v24, v29
	v_xor_b32_e32 v25, 2, v215
	v_xor_b32_e32 v28, 4, v215
	v_cndmask_b32_e32 v24, v215, v24, vcc
	v_cmp_lt_i32_e32 vcc, v25, v29
	v_lshlrev_b32_e32 v24, 2, v24
	s_nop 0
	v_cndmask_b32_e32 v25, v215, v25, vcc
	v_cmp_lt_i32_e32 vcc, v28, v29
	v_lshlrev_b32_e32 v25, 2, v25
	s_nop 0
	v_cndmask_b32_e32 v28, v215, v28, vcc
	v_cmp_lt_i32_e32 vcc, v36, v29
	v_lshlrev_b32_e32 v28, 2, v28
	s_nop 0
	v_cndmask_b32_e32 v29, v215, v36, vcc
	ds_bpermute_b32 v36, v24, v0
	v_lshlrev_b32_e32 v29, 2, v29
	s_waitcnt lgkmcnt(0)
	v_add_f32_e32 v0, v0, v36
	ds_bpermute_b32 v36, v25, v0
	s_waitcnt lgkmcnt(0)
	v_add_f32_e32 v0, v0, v36
	ds_bpermute_b32 v36, v28, v0
	s_waitcnt lgkmcnt(0)
	v_add_f32_e32 v0, v0, v36
	ds_bpermute_b32 v36, v29, v0
	s_and_saveexec_b64 s[20:21], s[6:7]
	s_cbranch_execz .LBB0_1466
	v_lshlrev_b64 v[10:11], 7, v[10:11]
	v_lshl_add_u64 v[10:11], s[18:19], 0, v[10:11]
	s_waitcnt lgkmcnt(0)
	v_add_f32_e32 v0, v0, v36
	global_store_dword v[10:11], v0, off
